# spatial-gating epilogue: U read-modify-write widened from 8+8 dwordx2 to 4+4 dwordx4 per group via v_permlane32_swap pairs (strategy 7.3)
# speedup vs baseline: 1.0071x; 1.0071x over previous
; #define LDSP(T, p) ((__attribute__((address_space(3))) T*)(p))
; DI unsigned pk2(float lo, float hi) { bf2_t v = __builtin_convertvector((f32x2){lo, hi}, bf2_t); return __builtin_bit_cast(unsigned, v); }
; DI float bf_lo(unsigned u) { return __uint_as_float(u << 16); }
; DI void sg_phase(const Params& p, lds_t* shm) {
;     ...
; #pragma unroll
;       for (int i = 0; i < 4; ++i) {
;         const int idx = tid + 512 * i, row = idx >> 4, ch = idx & 15; const int c0 = g * 128 + ch * 8;
;         const u32x4 v = raw[i];
;         const float mu = stats[2 * row], rs = stats[2 * row + 1];
;         const f32x4 g0 = *(const f32x4*)(p.ln_g + c0), g1 = *(const f32x4*)(p.ln_g + c0 + 4), b0 = *(const f32x4*)(p.ln_b + c0), b1 = *(const f32x4*)(p.ln_b + c0 + 4);
;         u32x4 o;
;         o.x = pk2((bf_lo(v.x) - mu) * rs * g0[0] + b0[0], (bf_hi(v.x) - mu) * rs * g0[1] + b0[1]);
;         o.y = pk2((bf_lo(v.y) - mu) * rs * g0[2] + b0[2], (bf_hi(v.y) - mu) * rs * g0[3] + b0[3]);
;         o.z = pk2((bf_lo(v.z) - mu) * rs * g1[0] + b1[0], (bf_hi(v.z) - mu) * rs * g1[1] + b1[1]);
;         o.w = pk2((bf_lo(v.w) - mu) * rs * g1[2] + b1[2], (bf_hi(v.w) - mu) * rs * g1[3] + b1[3]);
;         *LDSP(u32x4, shm + off_a(row, ch)) = o;
;       }
;       if (g + 1 < 8) {
; #pragma unroll
;         for (int i = 0; i < 4; ++i) { const int idx = tid + 512 * i, row = idx >> 4, ch = idx & 15; raw[i] = *(const u32x4*)(Vs + (size_t)(w * 128 + row) * DM + (g + 1) * 128 + ch * 8); }
;     ...
;       const bf16_t* wrow = wm + ((size_t)(g * 128 + ib * 32 + l31)) * 128 + 8 * h;
;       for (int ks = 0; ks < nks; ++ks) {
;         const bf16x8 bfr = *(const bf16x8*)(wrow + 16 * ks);
; #pragma unroll
;         for (int cc = 0; cc < 2; ++cc) {
;           const unsigned chb = 4 * (2 * chalf + cc) + 2 * blk + (pp >> 1);
;           const bf16x8 af = tr_pair(shm + off_a(16 * ks + 8 * h + q4, chb) + 8 * (pp & 1), shm + off_a(16 * ks + 8 * h + 4 + q4, chb) + 8 * (pp & 1));
;           acc[cc] = MFMA32(af, bfr, acc[cc]);
;         }
;       }
;       const int tok = w * 128 + ib * 32 + l31; const float bias = p.sg_b[g * 128 + ib * 32 + l31];
; #pragma unroll
;       for (int cc = 0; cc < 2; ++cc)
; #pragma unroll
;         for (int g4 = 0; g4 < 4; ++g4) {
;           bf16_t* up = U + (size_t)tok * DM + g * 128 + 32 * (2 * chalf + cc) + 8 * g4 + 4 * h;
;           const u32x2 uu = *(const u32x2*)up; f32x4 o;
.LBB0_396:
	s_lshl_b32 s1, s0, 7
	v_or_b32_e32 v48, s1, v77
	v_lshlrev_b64 v[0:1], 2, v[48:49]
	v_lshl_add_u64 v[8:9], s[40:41], 0, v[0:1]
	s_waitcnt lgkmcnt(2)
	v_lshl_add_u64 v[12:13], s[42:43], 0, v[0:1]
	s_waitcnt lgkmcnt(0)
	s_barrier
	global_load_dwordx4 v[0:3], v[12:13], off
	global_load_dwordx4 v[4:7], v[8:9], off
	s_nop 0
	global_load_dwordx4 v[8:11], v[8:9], off offset:16
	s_nop 0
	global_load_dwordx4 v[12:15], v[12:13], off offset:16
	ds_read_b64 v[16:17], v91 offset:32768
	s_waitcnt vmcnt(7)
	v_lshlrev_b32_e32 v18, 16, v32
	v_and_b32_e32 v19, 0xffff0000, v32
	v_lshlrev_b32_e32 v20, 16, v33
	v_and_b32_e32 v21, 0xffff0000, v33
	v_lshlrev_b32_e32 v22, 16, v34
	v_and_b32_e32 v23, 0xffff0000, v34
	v_lshlrev_b32_e32 v24, 16, v35
	v_and_b32_e32 v25, 0xffff0000, v35
	s_waitcnt lgkmcnt(0)
	v_pk_add_f32 v[18:19], v[18:19], v[16:17] op_sel_hi:[1,0] neg_lo:[0,1] neg_hi:[0,1]
	v_pk_add_f32 v[20:21], v[20:21], v[16:17] op_sel_hi:[1,0] neg_lo:[0,1] neg_hi:[0,1]
	v_pk_add_f32 v[22:23], v[22:23], v[16:17] op_sel_hi:[1,0] neg_lo:[0,1] neg_hi:[0,1]
	v_pk_add_f32 v[24:25], v[24:25], v[16:17] op_sel_hi:[1,0] neg_lo:[0,1] neg_hi:[0,1]
	v_pk_mul_f32 v[18:19], v[16:17], v[18:19] op_sel:[1,0]
	v_pk_mul_f32 v[20:21], v[16:17], v[20:21] op_sel:[1,0]
	v_pk_mul_f32 v[22:23], v[16:17], v[22:23] op_sel:[1,0]
	v_pk_mul_f32 v[16:17], v[16:17], v[24:25] op_sel:[1,0]
	s_waitcnt vmcnt(6)
	v_lshlrev_b32_e32 v26, 16, v36
	v_and_b32_e32 v27, 0xffff0000, v36
	v_lshlrev_b32_e32 v28, 16, v37
	v_and_b32_e32 v29, 0xffff0000, v37
	v_lshlrev_b32_e32 v30, 16, v38
	v_and_b32_e32 v31, 0xffff0000, v38
	v_lshlrev_b32_e32 v68, 16, v39
	v_and_b32_e32 v69, 0xffff0000, v39
	s_waitcnt vmcnt(5)
	v_lshlrev_b32_e32 v100, 16, v40
	v_and_b32_e32 v101, 0xffff0000, v40
	v_lshlrev_b32_e32 v102, 16, v41
	v_and_b32_e32 v103, 0xffff0000, v41
	v_lshlrev_b32_e32 v104, 16, v42
	v_and_b32_e32 v105, 0xffff0000, v42
	s_mov_b32 s4, s0
	s_add_i32 s0, s0, 1
	s_cmp_eq_u32 s4, 7
	s_waitcnt vmcnt(2)
	v_pk_fma_f32 v[18:19], v[18:19], v[4:5], v[0:1]
	v_pk_fma_f32 v[20:21], v[20:21], v[6:7], v[2:3]
	s_waitcnt vmcnt(0)
	v_pk_fma_f32 v[22:23], v[22:23], v[8:9], v[12:13]
	v_pk_fma_f32 v[24:25], v[16:17], v[10:11], v[14:15]
	v_cvt_pk_bf16_f32 v16, v18, v19
	v_cvt_pk_bf16_f32 v17, v20, v21
	v_cvt_pk_bf16_f32 v18, v22, v23
	v_cvt_pk_bf16_f32 v19, v24, v25
	ds_write_b128 v92, v[16:19]
	ds_read_b64 v[16:17], v93 offset:32768
	v_lshlrev_b32_e32 v20, 16, v43
	v_and_b32_e32 v21, 0xffff0000, v43
	v_lshlrev_b32_e32 v22, 16, v44
	v_and_b32_e32 v23, 0xffff0000, v44
	s_waitcnt lgkmcnt(0)
	v_pk_add_f32 v[18:19], v[26:27], v[16:17] op_sel_hi:[1,0] neg_lo:[0,1] neg_hi:[0,1]
	v_pk_add_f32 v[24:25], v[28:29], v[16:17] op_sel_hi:[1,0] neg_lo:[0,1] neg_hi:[0,1]
	v_pk_add_f32 v[26:27], v[30:31], v[16:17] op_sel_hi:[1,0] neg_lo:[0,1] neg_hi:[0,1]
	v_pk_add_f32 v[28:29], v[68:69], v[16:17] op_sel_hi:[1,0] neg_lo:[0,1] neg_hi:[0,1]
	v_pk_mul_f32 v[18:19], v[16:17], v[18:19] op_sel:[1,0]
	v_pk_mul_f32 v[24:25], v[16:17], v[24:25] op_sel:[1,0]
	v_pk_mul_f32 v[26:27], v[16:17], v[26:27] op_sel:[1,0]
	v_pk_mul_f32 v[16:17], v[16:17], v[28:29] op_sel:[1,0]
	v_pk_fma_f32 v[18:19], v[4:5], v[18:19], v[0:1]
	v_pk_fma_f32 v[24:25], v[6:7], v[24:25], v[2:3]
	v_pk_fma_f32 v[26:27], v[8:9], v[26:27], v[12:13]
	v_pk_fma_f32 v[28:29], v[10:11], v[16:17], v[14:15]
	v_cvt_pk_bf16_f32 v16, v18, v19
	v_cvt_pk_bf16_f32 v17, v24, v25
	v_cvt_pk_bf16_f32 v18, v26, v27
	v_cvt_pk_bf16_f32 v19, v28, v29
	ds_write_b128 v94, v[16:19]
	ds_read_b64 v[16:17], v95 offset:32768
	v_lshlrev_b32_e32 v24, 16, v45
	v_and_b32_e32 v25, 0xffff0000, v45
	v_lshlrev_b32_e32 v26, 16, v46
	v_and_b32_e32 v27, 0xffff0000, v46
	s_waitcnt lgkmcnt(0)
	v_pk_add_f32 v[18:19], v[100:101], v[16:17] op_sel_hi:[1,0] neg_lo:[0,1] neg_hi:[0,1]
	v_pk_add_f32 v[28:29], v[102:103], v[16:17] op_sel_hi:[1,0] neg_lo:[0,1] neg_hi:[0,1]
	v_pk_add_f32 v[30:31], v[104:105], v[16:17] op_sel_hi:[1,0] neg_lo:[0,1] neg_hi:[0,1]
	v_pk_add_f32 v[20:21], v[20:21], v[16:17] op_sel_hi:[1,0] neg_lo:[0,1] neg_hi:[0,1]
	v_pk_mul_f32 v[18:19], v[16:17], v[18:19] op_sel:[1,0]
	v_pk_mul_f32 v[28:29], v[16:17], v[28:29] op_sel:[1,0]
	v_pk_mul_f32 v[30:31], v[16:17], v[30:31] op_sel:[1,0]
	v_pk_mul_f32 v[16:17], v[16:17], v[20:21] op_sel:[1,0]
	v_pk_fma_f32 v[18:19], v[4:5], v[18:19], v[0:1]
	v_pk_fma_f32 v[20:21], v[6:7], v[28:29], v[2:3]
	v_pk_fma_f32 v[28:29], v[8:9], v[30:31], v[12:13]
	v_pk_fma_f32 v[30:31], v[10:11], v[16:17], v[14:15]
	v_cvt_pk_bf16_f32 v16, v18, v19
	v_cvt_pk_bf16_f32 v17, v20, v21
	v_cvt_pk_bf16_f32 v18, v28, v29
	v_cvt_pk_bf16_f32 v19, v30, v31
	ds_write_b128 v96, v[16:19]
	ds_read_b64 v[16:17], v97 offset:32768
	v_lshlrev_b32_e32 v18, 16, v47
	v_and_b32_e32 v19, 0xffff0000, v47
	s_waitcnt lgkmcnt(0)
	v_pk_add_f32 v[20:21], v[22:23], v[16:17] op_sel_hi:[1,0] neg_lo:[0,1] neg_hi:[0,1]
	v_pk_add_f32 v[22:23], v[24:25], v[16:17] op_sel_hi:[1,0] neg_lo:[0,1] neg_hi:[0,1]
	v_pk_add_f32 v[24:25], v[26:27], v[16:17] op_sel_hi:[1,0] neg_lo:[0,1] neg_hi:[0,1]
	v_pk_add_f32 v[18:19], v[18:19], v[16:17] op_sel_hi:[1,0] neg_lo:[0,1] neg_hi:[0,1]
	v_pk_mul_f32 v[20:21], v[16:17], v[20:21] op_sel:[1,0]
	v_pk_mul_f32 v[22:23], v[16:17], v[22:23] op_sel:[1,0]
	v_pk_mul_f32 v[24:25], v[16:17], v[24:25] op_sel:[1,0]
	v_pk_mul_f32 v[16:17], v[16:17], v[18:19] op_sel:[1,0]
	v_pk_fma_f32 v[0:1], v[4:5], v[20:21], v[0:1]
	v_pk_fma_f32 v[2:3], v[6:7], v[22:23], v[2:3]
	v_pk_fma_f32 v[4:5], v[8:9], v[24:25], v[12:13]
	v_pk_fma_f32 v[6:7], v[10:11], v[16:17], v[14:15]
	v_cvt_pk_bf16_f32 v0, v0, v1
	v_cvt_pk_bf16_f32 v1, v2, v3
	v_cvt_pk_bf16_f32 v2, v4, v5
	v_cvt_pk_bf16_f32 v3, v6, v7
	ds_write_b128 v98, v[0:3]
	v_or_b32_e32 v192, s1, v79
	v_mov_b32_e32 v193, 0
	v_lshl_add_u64 v[194:195], v[192:193], 2, s[46:47]
	v_lshlrev_b64 v[192:193], 8, v[192:193]
	v_lshl_add_u64 v[192:193], v[54:55], 0, v[192:193]
	global_load_dwordx4 v[160:163], v[192:193], off
	global_load_dwordx4 v[164:167], v[192:193], off offset:32
	global_load_dwordx4 v[168:171], v[192:193], off offset:64
	global_load_dwordx4 v[172:175], v[192:193], off offset:96
	global_load_dwordx4 v[176:179], v[192:193], off offset:128
	global_load_dwordx4 v[180:183], v[192:193], off offset:160
	global_load_dwordx4 v[184:187], v[192:193], off offset:192
	global_load_dwordx4 v[188:191], v[192:193], off offset:224
	global_load_dword v194, v[194:195], off
	s_lshl_b32 s8, s1, 1
	v_lshl_add_u64 v[130:131], v[66:67], 0, s[8:9]
	v_mbcnt_lo_u32_b32 v216, -1, 0
	v_mbcnt_hi_u32_b32 v216, -1, v216
	v_and_b32_e32 v216, 32, v216
	v_lshrrev_b32_e32 v216, 2, v216
	v_mov_b32_e32 v217, 0
	v_lshl_add_u64 v[130:131], v[130:131], 0, v[216:217]
	global_load_dwordx4 v[196:199], v[130:131], off
	global_load_dwordx4 v[200:203], v[130:131], off offset:32
	global_load_dwordx4 v[204:207], v[130:131], off offset:64
	global_load_dwordx4 v[208:211], v[130:131], off offset:96
	s_cmp_eq_u32 s4, 7
	s_cbranch_scc1 .Lsg_dummy
; DI void sg_phase(const Params& p, lds_t* shm) {
;     ...
;       if (g + 1 < 8) {
; #pragma unroll
;         for (int i = 0; i < 4; ++i) { const int idx = tid + 512 * i, row = idx >> 4, ch = idx & 15; raw[i] = *(const u32x4*)(Vs + (size_t)(w * 128 + row) * DM + (g + 1) * 128 + ch * 8); }
;       }
	s_lshl_b32 s8, s0, 8
	v_lshl_add_u64 v[0:1], v[52:53], 0, s[8:9]
	v_lshl_add_u64 v[2:3], v[0:1], 0, v[58:59]
	v_lshl_add_u64 v[4:5], v[0:1], 0, v[60:61]
	v_lshl_add_u64 v[6:7], v[0:1], 0, v[62:63]
	v_lshl_add_u64 v[0:1], v[0:1], 0, v[64:65]
	global_load_dwordx4 v[32:35], v[2:3], off
	global_load_dwordx4 v[36:39], v[4:5], off
	global_load_dwordx4 v[40:43], v[6:7], off
	global_load_dwordx4 v[44:47], v[0:1], off
	s_branch .LBB0_398

; #define MFMA32(a, b, c) __builtin_amdgcn_mfma_f32_32x32x16_bf16((a), (b), (c), 0, 0, 0)
; DI void sg_phase(const Params& p, lds_t* shm) {
;     ...
;       const int ib = wid & 3, chalf = wid >> 2, nks = (ib < 2) ? 4 : 8;
;       f32x16 acc[2];
; #pragma unroll
;       for (int cc = 0; cc < 2; ++cc)
; #pragma unroll
;         for (int i = 0; i < 16; ++i) acc[cc][i] = 0.f;
;       const bf16_t* wrow = wm + ((size_t)(g * 128 + ib * 32 + l31)) * 128 + 8 * h;
;       for (int ks = 0; ks < nks; ++ks) {
;         const bf16x8 bfr = *(const bf16x8*)(wrow + 16 * ks);
; #pragma unroll
;         for (int cc = 0; cc < 2; ++cc) {
;           const unsigned chb = 4 * (2 * chalf + cc) + 2 * blk + (pp >> 1);
;           const bf16x8 af = tr_pair(shm + off_a(16 * ks + 8 * h + q4, chb) + 8 * (pp & 1), shm + off_a(16 * ks + 8 * h + 4 + q4, chb) + 8 * (pp & 1));
;           acc[cc] = MFMA32(af, bfr, acc[cc]);
;         }
;       }
.LBB0_398:
	v_readfirstlane_b32 s4, v78
	v_or_b32_e32 v48, s1, v79
	v_lshlrev_b64 v[0:1], 8, v[48:49]
	v_mov_b32_e32 v16, 0
	v_lshl_add_u64 v[68:69], v[54:55], 0, v[0:1]
	s_mov_b32 s8, 0
	s_mov_b64 s[6:7], 0
	v_mov_b32_e32 v100, v90
	v_mov_b32_e32 v101, v78
	v_mov_b32_e32 v17, v16
	v_mov_b32_e32 v18, v16
	v_mov_b32_e32 v19, v16
	v_mov_b32_e32 v20, v16
	v_mov_b32_e32 v21, v16
	v_mov_b32_e32 v22, v16
	v_mov_b32_e32 v23, v16
	v_mov_b32_e32 v24, v16
	v_mov_b32_e32 v25, v16
	v_mov_b32_e32 v26, v16
	v_mov_b32_e32 v27, v16
	v_mov_b32_e32 v28, v16
	v_mov_b32_e32 v29, v16
	v_mov_b32_e32 v30, v16
	v_mov_b32_e32 v31, v16
	v_mov_b32_e32 v0, v16
	v_mov_b32_e32 v1, v16
	v_mov_b32_e32 v2, v16
	v_mov_b32_e32 v3, v16
	v_mov_b32_e32 v4, v16
	v_mov_b32_e32 v5, v16
	v_mov_b32_e32 v6, v16
	v_mov_b32_e32 v7, v16
	v_mov_b32_e32 v8, v16
	v_mov_b32_e32 v9, v16
	v_mov_b32_e32 v10, v16
	v_mov_b32_e32 v11, v16
	v_mov_b32_e32 v12, v16
	v_mov_b32_e32 v13, v16
	v_mov_b32_e32 v14, v16
	v_mov_b32_e32 v15, v16
	s_waitcnt lgkmcnt(0)
	s_barrier
	v_mov_b32_e32 v122, v89
	v_and_b32_e32 v123, 0xfffff800, v100
	v_lshrrev_b32_e32 v122, 2, v122
	v_add_u32_e32 v125, v88, v123
	v_bitop3_b32 v124, v122, v81, 1 bitop3:0x36
	ds_read_b64_tr_b16 v[106:107], v125
	v_lshlrev_b32_e32 v124, 4, v124
	v_and_b32_e32 v124, 48, v124
	v_add3_u32 v123, v82, v123, v124
	v_add3_u32 v126, v123, v83, v80
	ds_read_b64_tr_b16 v[108:109], v126 offset:256
	ds_read_b64_tr_b16 v[110:111], v125 offset:512
	ds_read_b64_tr_b16 v[112:113], v126 offset:768
	v_add_u32_e32 v100, 0x1000, v100
	v_add_u32_e32 v122, 16, v89
	v_and_b32_e32 v123, 0xfffff800, v100
	v_lshrrev_b32_e32 v122, 2, v122
	v_add_u32_e32 v125, v88, v123
	v_bitop3_b32 v124, v122, v81, 1 bitop3:0x36
	ds_read_b64_tr_b16 v[114:115], v125
	v_lshlrev_b32_e32 v124, 4, v124
	v_and_b32_e32 v124, 48, v124
	v_add3_u32 v123, v82, v123, v124
	v_add3_u32 v126, v123, v83, v80
	ds_read_b64_tr_b16 v[116:117], v126 offset:256
	ds_read_b64_tr_b16 v[118:119], v125 offset:512
	ds_read_b64_tr_b16 v[120:121], v126 offset:768
	v_add_u32_e32 v100, 0x1000, v100
	s_waitcnt vmcnt(16) lgkmcnt(4)
	v_mfma_f32_32x32x16_bf16 v[16:31], v[106:109], v[160:163], v[16:31]
	v_mfma_f32_32x32x16_bf16 v[0:15], v[110:113], v[160:163], v[0:15]
	v_add_u32_e32 v122, 32, v89
	v_and_b32_e32 v123, 0xfffff800, v100
	v_lshrrev_b32_e32 v122, 2, v122
	v_add_u32_e32 v125, v88, v123
	v_bitop3_b32 v124, v122, v81, 1 bitop3:0x36
	ds_read_b64_tr_b16 v[106:107], v125
	v_lshlrev_b32_e32 v124, 4, v124
	v_and_b32_e32 v124, 48, v124
	v_add3_u32 v123, v82, v123, v124
	v_add3_u32 v126, v123, v83, v80
	ds_read_b64_tr_b16 v[108:109], v126 offset:256
	ds_read_b64_tr_b16 v[110:111], v125 offset:512
	ds_read_b64_tr_b16 v[112:113], v126 offset:768
	v_add_u32_e32 v100, 0x1000, v100
	s_waitcnt vmcnt(15) lgkmcnt(4)
	v_mfma_f32_32x32x16_bf16 v[16:31], v[114:117], v[164:167], v[16:31]
	v_mfma_f32_32x32x16_bf16 v[0:15], v[118:121], v[164:167], v[0:15]
	v_add_u32_e32 v122, 48, v89
	v_and_b32_e32 v123, 0xfffff800, v100
	v_lshrrev_b32_e32 v122, 2, v122
	v_add_u32_e32 v125, v88, v123
	v_bitop3_b32 v124, v122, v81, 1 bitop3:0x36
	ds_read_b64_tr_b16 v[114:115], v125
	v_lshlrev_b32_e32 v124, 4, v124
	v_and_b32_e32 v124, 48, v124
	v_add3_u32 v123, v82, v123, v124
	v_add3_u32 v126, v123, v83, v80
	ds_read_b64_tr_b16 v[116:117], v126 offset:256
	ds_read_b64_tr_b16 v[118:119], v125 offset:512
	ds_read_b64_tr_b16 v[120:121], v126 offset:768
	v_add_u32_e32 v100, 0x1000, v100
	s_waitcnt vmcnt(14) lgkmcnt(4)
	v_mfma_f32_32x32x16_bf16 v[16:31], v[106:109], v[168:171], v[16:31]
	v_mfma_f32_32x32x16_bf16 v[0:15], v[110:113], v[168:171], v[0:15]
	s_cmp_eq_u32 s4, 4
	s_cbranch_scc1 .Lsg_tail3
	v_add_u32_e32 v122, 64, v89
	v_and_b32_e32 v123, 0xfffff800, v100
	v_lshrrev_b32_e32 v122, 2, v122
	v_add_u32_e32 v125, v88, v123
	v_bitop3_b32 v124, v122, v81, 1 bitop3:0x36
	ds_read_b64_tr_b16 v[106:107], v125
	v_lshlrev_b32_e32 v124, 4, v124
	v_and_b32_e32 v124, 48, v124
	v_add3_u32 v123, v82, v123, v124
	v_add3_u32 v126, v123, v83, v80
	ds_read_b64_tr_b16 v[108:109], v126 offset:256
	ds_read_b64_tr_b16 v[110:111], v125 offset:512
	ds_read_b64_tr_b16 v[112:113], v126 offset:768
	v_add_u32_e32 v100, 0x1000, v100
	s_waitcnt vmcnt(13) lgkmcnt(4)
	v_mfma_f32_32x32x16_bf16 v[16:31], v[114:117], v[172:175], v[16:31]
	v_mfma_f32_32x32x16_bf16 v[0:15], v[118:121], v[172:175], v[0:15]
	v_add_u32_e32 v122, 80, v89
	v_and_b32_e32 v123, 0xfffff800, v100
	v_lshrrev_b32_e32 v122, 2, v122
	v_add_u32_e32 v125, v88, v123
	v_bitop3_b32 v124, v122, v81, 1 bitop3:0x36
	ds_read_b64_tr_b16 v[114:115], v125
	v_lshlrev_b32_e32 v124, 4, v124
	v_and_b32_e32 v124, 48, v124
	v_add3_u32 v123, v82, v123, v124
	v_add3_u32 v126, v123, v83, v80
	ds_read_b64_tr_b16 v[116:117], v126 offset:256
	ds_read_b64_tr_b16 v[118:119], v125 offset:512
	ds_read_b64_tr_b16 v[120:121], v126 offset:768
	v_add_u32_e32 v100, 0x1000, v100
	s_waitcnt vmcnt(12) lgkmcnt(4)
	v_mfma_f32_32x32x16_bf16 v[16:31], v[106:109], v[176:179], v[16:31]
	v_mfma_f32_32x32x16_bf16 v[0:15], v[110:113], v[176:179], v[0:15]
	v_add_u32_e32 v122, 96, v89
	v_and_b32_e32 v123, 0xfffff800, v100
	v_lshrrev_b32_e32 v122, 2, v122
	v_add_u32_e32 v125, v88, v123
	v_bitop3_b32 v124, v122, v81, 1 bitop3:0x36
	ds_read_b64_tr_b16 v[106:107], v125
	v_lshlrev_b32_e32 v124, 4, v124
	v_and_b32_e32 v124, 48, v124
	v_add3_u32 v123, v82, v123, v124
	v_add3_u32 v126, v123, v83, v80
	ds_read_b64_tr_b16 v[108:109], v126 offset:256
	ds_read_b64_tr_b16 v[110:111], v125 offset:512
	ds_read_b64_tr_b16 v[112:113], v126 offset:768
	v_add_u32_e32 v100, 0x1000, v100
	s_waitcnt vmcnt(11) lgkmcnt(4)
	v_mfma_f32_32x32x16_bf16 v[16:31], v[114:117], v[180:183], v[16:31]
	v_mfma_f32_32x32x16_bf16 v[0:15], v[118:121], v[180:183], v[0:15]
	v_add_u32_e32 v122, 112, v89
	v_and_b32_e32 v123, 0xfffff800, v100
	v_lshrrev_b32_e32 v122, 2, v122
	v_add_u32_e32 v125, v88, v123
	v_bitop3_b32 v124, v122, v81, 1 bitop3:0x36
	ds_read_b64_tr_b16 v[114:115], v125
	v_lshlrev_b32_e32 v124, 4, v124
	v_and_b32_e32 v124, 48, v124
	v_add3_u32 v123, v82, v123, v124
	v_add3_u32 v126, v123, v83, v80
	ds_read_b64_tr_b16 v[116:117], v126 offset:256
	ds_read_b64_tr_b16 v[118:119], v125 offset:512
	ds_read_b64_tr_b16 v[120:121], v126 offset:768
	v_add_u32_e32 v100, 0x1000, v100
	s_waitcnt vmcnt(10) lgkmcnt(4)
	v_mfma_f32_32x32x16_bf16 v[16:31], v[106:109], v[184:187], v[16:31]
	v_mfma_f32_32x32x16_bf16 v[0:15], v[110:113], v[184:187], v[0:15]
	s_waitcnt vmcnt(9) lgkmcnt(0)
	v_mfma_f32_32x32x16_bf16 v[16:31], v[114:117], v[188:191], v[16:31]
	v_mfma_f32_32x32x16_bf16 v[0:15], v[118:121], v[188:191], v[0:15]
	s_branch .Lsg_done
; DI float bf_lo(unsigned u) { return __uint_as_float(u << 16); }
; DI float bf_hi(unsigned u) { return __uint_as_float(u & 0xffff0000u); }
; #define MFMA32(a, b, c) __builtin_amdgcn_mfma_f32_32x32x16_bf16((a), (b), (c), 0, 0, 0)
; DI void st_bf4(bf16_t* p, f32x4 v) { u32x2 w; w.x = pk2(v[0], v[1]); w.y = pk2(v[2], v[3]); *(u32x2*)p = w; }
; DI void sg_phase(const Params& p, lds_t* shm) {
;     ...
; #pragma unroll
;         for (int cc = 0; cc < 2; ++cc) {
;           const unsigned chb = 4 * (2 * chalf + cc) + 2 * blk + (pp >> 1);
;           const bf16x8 af = tr_pair(shm + off_a(16 * ks + 8 * h + q4, chb) + 8 * (pp & 1), shm + off_a(16 * ks + 8 * h + 4 + q4, chb) + 8 * (pp & 1));
;           acc[cc] = MFMA32(af, bfr, acc[cc]);
;         }
;       }
;       const int tok = w * 128 + ib * 32 + l31; const float bias = p.sg_b[g * 128 + ib * 32 + l31];
; #pragma unroll
;       for (int cc = 0; cc < 2; ++cc)
; #pragma unroll
;         for (int g4 = 0; g4 < 4; ++g4) {
;           bf16_t* up = U + (size_t)tok * DM + g * 128 + 32 * (2 * chalf + cc) + 8 * g4 + 4 * h;
;           const u32x2 uu = *(const u32x2*)up; f32x4 o;
;           o[0] = bf_lo(uu.x) * (acc[cc][4 * g4 + 0] + bias); o[1] = bf_hi(uu.x) * (acc[cc][4 * g4 + 1] + bias);
;           o[2] = bf_lo(uu.y) * (acc[cc][4 * g4 + 2] + bias); o[3] = bf_hi(uu.y) * (acc[cc][4 * g4 + 3] + bias);
;           st_bf4(up, o);
;         }
.Lsg_tail3:
	s_waitcnt vmcnt(13) lgkmcnt(0)
	v_mfma_f32_32x32x16_bf16 v[16:31], v[114:117], v[172:175], v[16:31]
	v_mfma_f32_32x32x16_bf16 v[0:15], v[118:121], v[172:175], v[0:15]
.Lsg_done:
	s_or_b64 exec, exec, s[6:7]
	s_lshl_b32 s8, s1, 1
	v_lshl_add_u64 v[68:69], v[66:67], 0, s[8:9]
	v_lshl_add_u64 v[68:69], v[68:69], 0, v[216:217]
	s_waitcnt vmcnt(8)
	s_nop 7
	s_nop 7
	v_pk_add_f32 v[16:17], v[16:17], v[194:195] op_sel_hi:[1,0]
	v_pk_add_f32 v[18:19], v[18:19], v[194:195] op_sel_hi:[1,0]
	v_pk_add_f32 v[20:21], v[20:21], v[194:195] op_sel_hi:[1,0]
	v_pk_add_f32 v[22:23], v[22:23], v[194:195] op_sel_hi:[1,0]
	v_pk_add_f32 v[24:25], v[24:25], v[194:195] op_sel_hi:[1,0]
	v_pk_add_f32 v[26:27], v[26:27], v[194:195] op_sel_hi:[1,0]
	v_pk_add_f32 v[28:29], v[28:29], v[194:195] op_sel_hi:[1,0]
	v_pk_add_f32 v[30:31], v[30:31], v[194:195] op_sel_hi:[1,0]
	v_pk_add_f32 v[0:1], v[0:1], v[194:195] op_sel_hi:[1,0]
	v_pk_add_f32 v[2:3], v[2:3], v[194:195] op_sel_hi:[1,0]
	v_pk_add_f32 v[4:5], v[4:5], v[194:195] op_sel_hi:[1,0]
	v_pk_add_f32 v[6:7], v[6:7], v[194:195] op_sel_hi:[1,0]
	v_pk_add_f32 v[8:9], v[8:9], v[194:195] op_sel_hi:[1,0]
	v_pk_add_f32 v[10:11], v[10:11], v[194:195] op_sel_hi:[1,0]
	v_pk_add_f32 v[12:13], v[12:13], v[194:195] op_sel_hi:[1,0]
	v_pk_add_f32 v[14:15], v[14:15], v[194:195] op_sel_hi:[1,0]
	s_nop 1
	v_permlane32_swap_b32_e32 v16, v20
	v_permlane32_swap_b32_e32 v17, v21
	v_permlane32_swap_b32_e32 v18, v22
	v_permlane32_swap_b32_e32 v19, v23
	v_permlane32_swap_b32_e32 v24, v28
	v_permlane32_swap_b32_e32 v25, v29
	v_permlane32_swap_b32_e32 v26, v30
	v_permlane32_swap_b32_e32 v27, v31
	v_permlane32_swap_b32_e32 v0, v4
	v_permlane32_swap_b32_e32 v1, v5
	v_permlane32_swap_b32_e32 v2, v6
	v_permlane32_swap_b32_e32 v3, v7
	v_permlane32_swap_b32_e32 v8, v12
	v_permlane32_swap_b32_e32 v9, v13
	v_permlane32_swap_b32_e32 v10, v14
	v_permlane32_swap_b32_e32 v11, v15
	s_waitcnt vmcnt(7)
	v_lshlrev_b32_e32 v100, 16, v196
	v_and_b32_e32 v101, 0xffff0000, v196
	v_lshlrev_b32_e32 v102, 16, v197
	v_and_b32_e32 v103, 0xffff0000, v197
	v_lshlrev_b32_e32 v104, 16, v198
	v_and_b32_e32 v105, 0xffff0000, v198
	v_lshlrev_b32_e32 v106, 16, v199
	v_and_b32_e32 v107, 0xffff0000, v199
	v_pk_mul_f32 v[16:17], v[16:17], v[100:101]
	v_pk_mul_f32 v[18:19], v[18:19], v[102:103]
	v_pk_mul_f32 v[20:21], v[20:21], v[104:105]
	v_pk_mul_f32 v[22:23], v[22:23], v[106:107]
	v_cvt_pk_bf16_f32 v16, v16, v17
	v_cvt_pk_bf16_f32 v17, v18, v19
	v_cvt_pk_bf16_f32 v18, v20, v21
	v_cvt_pk_bf16_f32 v19, v22, v23
	global_store_dwordx4 v[68:69], v[16:19], off
	s_waitcnt vmcnt(6)
	v_lshlrev_b32_e32 v108, 16, v200
	v_and_b32_e32 v109, 0xffff0000, v200
	v_lshlrev_b32_e32 v110, 16, v201
	v_and_b32_e32 v111, 0xffff0000, v201
	v_lshlrev_b32_e32 v112, 16, v202
	v_and_b32_e32 v113, 0xffff0000, v202
	v_lshlrev_b32_e32 v114, 16, v203
	v_and_b32_e32 v115, 0xffff0000, v203
	v_pk_mul_f32 v[24:25], v[24:25], v[108:109]
	v_pk_mul_f32 v[26:27], v[26:27], v[110:111]
	v_pk_mul_f32 v[28:29], v[28:29], v[112:113]
	v_pk_mul_f32 v[30:31], v[30:31], v[114:115]
	v_cvt_pk_bf16_f32 v24, v24, v25
	v_cvt_pk_bf16_f32 v25, v26, v27
	v_cvt_pk_bf16_f32 v26, v28, v29
	v_cvt_pk_bf16_f32 v27, v30, v31
	global_store_dwordx4 v[68:69], v[24:27], off offset:32
	s_waitcnt vmcnt(5)
	v_lshlrev_b32_e32 v100, 16, v204
	v_and_b32_e32 v101, 0xffff0000, v204
	v_lshlrev_b32_e32 v102, 16, v205
	v_and_b32_e32 v103, 0xffff0000, v205
	v_lshlrev_b32_e32 v104, 16, v206
	v_and_b32_e32 v105, 0xffff0000, v206
	v_lshlrev_b32_e32 v106, 16, v207
	v_and_b32_e32 v107, 0xffff0000, v207
	v_pk_mul_f32 v[0:1], v[0:1], v[100:101]
	v_pk_mul_f32 v[2:3], v[2:3], v[102:103]
	v_pk_mul_f32 v[4:5], v[4:5], v[104:105]
	v_pk_mul_f32 v[6:7], v[6:7], v[106:107]
	v_cvt_pk_bf16_f32 v0, v0, v1
	v_cvt_pk_bf16_f32 v1, v2, v3
	v_cvt_pk_bf16_f32 v2, v4, v5
	v_cvt_pk_bf16_f32 v3, v6, v7
	global_store_dwordx4 v[68:69], v[0:3], off offset:64
	s_waitcnt vmcnt(4)
	v_lshlrev_b32_e32 v108, 16, v208
	v_and_b32_e32 v109, 0xffff0000, v208
	v_lshlrev_b32_e32 v110, 16, v209
	v_and_b32_e32 v111, 0xffff0000, v209
	v_lshlrev_b32_e32 v112, 16, v210
	v_and_b32_e32 v113, 0xffff0000, v210
	v_lshlrev_b32_e32 v114, 16, v211
	v_and_b32_e32 v115, 0xffff0000, v211
	v_pk_mul_f32 v[8:9], v[8:9], v[108:109]
	v_pk_mul_f32 v[10:11], v[10:11], v[110:111]
	v_pk_mul_f32 v[12:13], v[12:13], v[112:113]
	v_pk_mul_f32 v[14:15], v[14:15], v[114:115]
	v_cvt_pk_bf16_f32 v8, v8, v9
	v_cvt_pk_bf16_f32 v9, v10, v11
	v_cvt_pk_bf16_f32 v10, v12, v13
	v_cvt_pk_bf16_f32 v11, v14, v15
	global_store_dwordx4 v[68:69], v[8:11], off offset:96
	s_cmp_eq_u32 s0, 8
	s_cbranch_scc0 .LBB0_396
	s_add_i32 s3, s3, s90
	s_cmpk_gt_i32 s3, 0xff
	s_cbranch_scc0 .LBB0_387
